# grid barrier, non-leader path: L1 invalidate issued right after the arrival atomic (completes during the wait) instead of after the release
# speedup vs baseline: 1.0148x; 1.0093x over previous
.LBB0_103:
	s_lshl_b32 s4, s33, 8
	s_mov_b64 s[6:7], exec
	s_add_u32 s4, s2, s4
	s_addc_u32 s5, s3, 0
	v_mbcnt_lo_u32_b32 v1, s6, 0
	s_add_u32 s4, s4, 0x19210000
	v_mbcnt_hi_u32_b32 v1, s7, v1
	s_addc_u32 s5, s5, 0
	v_cmp_eq_u32_e32 vcc, 0, v1
	s_and_saveexec_b64 s[10:11], vcc
	s_cbranch_execz .LBB0_105
	s_bcnt1_i32_b64 s6, s[6:7]
	v_mov_b32_e32 v3, s6
	v_mov_b32_e32 v4, 0x1000
	global_atomic_add v3, v4, v3, s[4:5] offset:1024 sc0
	buffer_inv sc1

.LBB0_118:
	s_or_b64 exec, exec, s[10:11]
	s_waitcnt vmcnt(0)
	s_waitcnt vmcnt(0)

.LBB0_165:
	s_lshl_b32 s10, s33, 8
	s_mov_b64 s[12:13], exec
	s_add_u32 s10, s6, s10
	s_addc_u32 s11, s7, 0
	v_mbcnt_lo_u32_b32 v1, s12, 0
	s_add_u32 s10, s10, 0x19210000
	v_mbcnt_hi_u32_b32 v1, s13, v1
	s_addc_u32 s11, s11, 0
	v_cmp_eq_u32_e32 vcc, 0, v1
	s_and_saveexec_b64 s[14:15], vcc
	s_cbranch_execz .LBB0_167
	s_bcnt1_i32_b64 s12, s[12:13]
	v_mov_b32_e32 v3, s12
	v_mov_b32_e32 v4, 0x1000
	global_atomic_add v3, v4, v3, s[10:11] offset:1024 sc0
	buffer_inv sc1

.LBB0_180:
	s_or_b64 exec, exec, s[14:15]
	s_waitcnt vmcnt(0)
	s_waitcnt vmcnt(0)

.LBB0_224:
	s_lshl_b32 s6, s33, 8
	s_mov_b64 s[10:11], exec
	s_add_u32 s6, s4, s6
	s_addc_u32 s7, s5, 0
	v_mbcnt_lo_u32_b32 v1, s10, 0
	s_add_u32 s6, s6, 0x19210000
	v_mbcnt_hi_u32_b32 v1, s11, v1
	s_addc_u32 s7, s7, 0
	v_cmp_eq_u32_e32 vcc, 0, v1
	s_and_saveexec_b64 s[12:13], vcc
	s_cbranch_execz .LBB0_226
	s_bcnt1_i32_b64 s10, s[10:11]
	v_mov_b32_e32 v3, s10
	v_mov_b32_e32 v4, 0x1000
	global_atomic_add v3, v4, v3, s[6:7] offset:1024 sc0
	buffer_inv sc1

.LBB0_239:
	s_or_b64 exec, exec, s[12:13]
	s_waitcnt vmcnt(0)
	s_waitcnt vmcnt(0)

.LBB0_991:
	s_lshl_b32 s16, s33, 8
	s_mov_b64 s[18:19], exec
	s_add_u32 s16, s2, s16
	s_addc_u32 s17, s3, 0
	v_mbcnt_lo_u32_b32 v1, s18, 0
	s_add_u32 s16, s16, 0x19210000
	v_mbcnt_hi_u32_b32 v1, s19, v1
	s_addc_u32 s17, s17, 0
	v_cmp_eq_u32_e32 vcc, 0, v1
	s_and_saveexec_b64 s[20:21], vcc
	s_cbranch_execz .LBB0_993
	s_bcnt1_i32_b64 s18, s[18:19]
	v_mov_b32_e32 v3, s18
	v_mov_b32_e32 v4, 0x1000
	global_atomic_add v3, v4, v3, s[16:17] offset:1024 sc0
	buffer_inv sc1

.LBB0_1006:
	s_or_b64 exec, exec, s[20:21]
	s_waitcnt vmcnt(0)
	s_waitcnt vmcnt(0)

.LBB0_1862:
	s_lshl_b32 s4, s33, 8
	s_mov_b64 s[6:7], exec
	s_add_u32 s4, s2, s4
	s_addc_u32 s5, s3, 0
	v_mbcnt_lo_u32_b32 v1, s6, 0
	s_add_u32 s4, s4, 0x19210000
	v_mbcnt_hi_u32_b32 v1, s7, v1
	s_addc_u32 s5, s5, 0
	v_cmp_eq_u32_e32 vcc, 0, v1
	s_and_saveexec_b64 s[12:13], vcc
	s_cbranch_execz .LBB0_1864
	s_bcnt1_i32_b64 s6, s[6:7]
	v_mov_b32_e32 v3, s6
	v_mov_b32_e32 v4, 0x1000
	global_atomic_add v3, v4, v3, s[4:5] offset:1024 sc0
	buffer_inv sc1

.LBB0_2130:
	s_lshl_b32 s4, s33, 8
	s_mov_b64 s[6:7], exec
	s_add_u32 s4, s2, s4
	s_addc_u32 s5, s3, 0
	v_mbcnt_lo_u32_b32 v1, s6, 0
	s_add_u32 s4, s4, 0x19210000
	v_mbcnt_hi_u32_b32 v1, s7, v1
	s_addc_u32 s5, s5, 0
	v_cmp_eq_u32_e32 vcc, 0, v1
	s_and_saveexec_b64 s[8:9], vcc
	s_cbranch_execz .LBB0_2132
	s_bcnt1_i32_b64 s6, s[6:7]
	v_mov_b32_e32 v3, s6
	v_mov_b32_e32 v4, 0x1000
	global_atomic_add v3, v4, v3, s[4:5] offset:1024 sc0
	buffer_inv sc1

.LBB0_2145:
	s_or_b64 exec, exec, s[8:9]
	s_waitcnt vmcnt(0)
	s_waitcnt vmcnt(0)

.LBB0_2449:
	s_lshl_b32 s6, s33, 8
	s_mov_b64 s[8:9], exec
	s_add_u32 s6, s2, s6
	s_addc_u32 s7, s3, 0
	v_mbcnt_lo_u32_b32 v1, s8, 0
	s_add_u32 s6, s6, 0x19210000
	v_mbcnt_hi_u32_b32 v1, s9, v1
	s_addc_u32 s7, s7, 0
	v_cmp_eq_u32_e32 vcc, 0, v1
	s_and_saveexec_b64 s[10:11], vcc
	s_cbranch_execz .LBB0_2451
	s_bcnt1_i32_b64 s8, s[8:9]
	v_mov_b32_e32 v3, s8
	v_mov_b32_e32 v4, 0x1000
	global_atomic_add v3, v4, v3, s[6:7] offset:1024 sc0
	buffer_inv sc1
